# phase 1: 256x128 block tiles (single-stage LDS, fragments in registers) for 80 of 84 column tiles, remainder on 128x128 path
# speedup vs baseline: 1.0483x; 1.0403x over previous
.LBB0_116:
	s_or_b64 exec, exec, s[0:1]
	s_add_u32 s0, s94, 0x15000000
	s_addc_u32 s1, s95, 0
	s_add_u32 s28, s94, 0x6c00000
	v_writelane_b32 v242, s0, 50
	s_addc_u32 s29, s95, 0
	v_mov_b32_e32 v0, v199
	v_writelane_b32 v242, s1, 51
	s_add_u32 s0, s94, 0xd000000
	s_addc_u32 s1, s95, 0
	v_writelane_b32 v242, s0, 52
	s_barrier
	s_nop 0
	v_writelane_b32 v242, s1, 53
	s_nop 0
	v_readlane_b32 s0, v242, 45
	v_readlane_b32 s1, v242, 46
	s_cmpk_gt_i32 s0, 0x29ff
	v_writelane_b32 v242, s58, 54
	s_nop 1
	v_writelane_b32 v242, s59, 55
	s_cbranch_scc1 .LBB0_246
	s_mov_b32 s91, 0
	s_cmp_lg_u32 s96, 0x200
	s_cbranch_scc1 .Lbig_skip
	v_lshrrev_b32_e32 v236, 3, v199
	v_lshrrev_b32_e32 v237, 4, v199
	v_xor_b32_e32 v237, v237, v199
	v_and_b32_e32 v237, 7, v237
	v_lshlrev_b32_e32 v237, 4, v237
	v_lshl_add_u32 v192, v236, 12, v237
	v_add_u32_e32 v193, 0x20000, v192
	v_add_u32_e32 v194, 0x40000, v192
	v_add_u32_e32 v195, 0x60000, v192
	v_and_b32_e32 v236, 15, v199
	v_bfe_u32 v237, v199, 4, 2
	v_lshrrev_b32_e32 v238, 1, v236
	v_lshlrev_b32_e32 v202, 3, v237
	v_xor_b32_e32 v237, v237, v238
	v_lshlrev_b32_e32 v237, 4, v237
	v_xor_b32_e32 v238, 64, v237
	v_lshrrev_b32_e32 v201, 7, v199
	v_lshl_add_u32 v201, v201, 7, v236
	v_lshlrev_b32_e32 v196, 7, v201
	v_bfe_u32 v198, v199, 6, 1
	v_lshl_add_u32 v202, v198, 7, v202
	v_lshl_add_u32 v198, v198, 6, v236
	v_lshlrev_b32_e32 v198, 7, v198
	v_add_u32_e32 v198, 0x8000, v198
	v_add_u32_e32 v197, v196, v238
	v_add_u32_e32 v200, v198, v238
	v_add_u32_e32 v196, v196, v237
	v_add_u32_e32 v198, v198, v237
	v_lshrrev_b32_e32 v236, 6, v199
	v_lshlrev_b32_e32 v236, 10, v236
	s_nop 0
	v_readfirstlane_b32 s32, v236
	v_readlane_b32 s90, v242, 45
	s_and_b32 s51, s90, 63
	s_lshl_b32 s51, s51, 20
	s_add_u32 s36, s94, s51
	s_addc_u32 s37, s95, 0
	s_add_u32 s36, s36, 0x15000000
	s_addc_u32 s37, s37, 0
	s_lshr_b32 s51, s90, 6
	s_lshl_b32 s51, s51, 19
	s_add_u32 s44, s94, s51
	s_addc_u32 s45, s95, 0
	s_add_u32 s44, s44, 0x19000000
	s_addc_u32 s45, s45, 0
	s_add_u32 s40, s36, 0x80000
	s_addc_u32 s41, s37, 0
	s_barrier
	s_add_u32 m0, s32, 0x0
	s_nop 0
	global_load_lds_dwordx4 v192, s[36:37]
	s_add_u32 m0, s32, 0x1000
	s_nop 0
	global_load_lds_dwordx4 v193, s[36:37]
	s_add_u32 m0, s32, 0x2000
	s_nop 0
	global_load_lds_dwordx4 v194, s[36:37]
	s_add_u32 m0, s32, 0x3000
	s_nop 0
	global_load_lds_dwordx4 v195, s[36:37]
	s_add_u32 m0, s32, 0x4000
	s_nop 0
	global_load_lds_dwordx4 v192, s[40:41]
	s_add_u32 m0, s32, 0x5000
	s_nop 0
	global_load_lds_dwordx4 v193, s[40:41]
	s_add_u32 m0, s32, 0x6000
	s_nop 0
	global_load_lds_dwordx4 v194, s[40:41]
	s_add_u32 m0, s32, 0x7000
	s_nop 0
	global_load_lds_dwordx4 v195, s[40:41]
	s_add_u32 m0, s32, 0x8000
	s_nop 0
	global_load_lds_dwordx4 v192, s[44:45]
	s_add_u32 m0, s32, 0x9000
	s_nop 0
	global_load_lds_dwordx4 v193, s[44:45]
	s_add_u32 m0, s32, 0xa000
	s_nop 0
	global_load_lds_dwordx4 v194, s[44:45]
	s_add_u32 m0, s32, 0xb000
	s_nop 0
	global_load_lds_dwordx4 v195, s[44:45]
	s_add_u32 s36, s36, 0x80
	s_addc_u32 s37, s37, 0
	s_add_u32 s40, s40, 0x80
	s_addc_u32 s41, s41, 0
	s_add_u32 s44, s44, 0x80
	s_addc_u32 s45, s45, 0
	s_waitcnt vmcnt(0)
.Lbig_tile:
	s_add_u32 s91, s90, 0x200
	s_and_b32 s51, s91, 63
	s_lshl_b32 s51, s51, 20
	s_add_u32 s46, s94, s51
	s_addc_u32 s47, s95, 0
	s_add_u32 s46, s46, 0x15000000
	s_addc_u32 s47, s47, 0
	s_lshr_b32 s51, s91, 6
	s_lshl_b32 s51, s51, 19
	s_add_u32 s48, s94, s51
	s_addc_u32 s49, s95, 0
	s_add_u32 s48, s48, 0x19000000
	s_addc_u32 s49, s49, 0
	v_mov_b32_e32 v0, 0
	v_mov_b32_e32 v1, 0
	v_mov_b32_e32 v2, 0
	v_mov_b32_e32 v3, 0
	v_mov_b32_e32 v4, 0
	v_mov_b32_e32 v5, 0
	v_mov_b32_e32 v6, 0
	v_mov_b32_e32 v7, 0
	v_mov_b32_e32 v8, 0
	v_mov_b32_e32 v9, 0
	v_mov_b32_e32 v10, 0
	v_mov_b32_e32 v11, 0
	v_mov_b32_e32 v12, 0
	v_mov_b32_e32 v13, 0
	v_mov_b32_e32 v14, 0
	v_mov_b32_e32 v15, 0
	v_mov_b32_e32 v16, 0
	v_mov_b32_e32 v17, 0
	v_mov_b32_e32 v18, 0
	v_mov_b32_e32 v19, 0
	v_mov_b32_e32 v20, 0
	v_mov_b32_e32 v21, 0
	v_mov_b32_e32 v22, 0
	v_mov_b32_e32 v23, 0
	v_mov_b32_e32 v24, 0
	v_mov_b32_e32 v25, 0
	v_mov_b32_e32 v26, 0
	v_mov_b32_e32 v27, 0
	v_mov_b32_e32 v28, 0
	v_mov_b32_e32 v29, 0
	v_mov_b32_e32 v30, 0
	v_mov_b32_e32 v31, 0
	v_mov_b32_e32 v32, 0
	v_mov_b32_e32 v33, 0
	v_mov_b32_e32 v34, 0
	v_mov_b32_e32 v35, 0
	v_mov_b32_e32 v36, 0
	v_mov_b32_e32 v37, 0
	v_mov_b32_e32 v38, 0
	v_mov_b32_e32 v39, 0
	v_mov_b32_e32 v40, 0
	v_mov_b32_e32 v41, 0
	v_mov_b32_e32 v42, 0
	v_mov_b32_e32 v43, 0
	v_mov_b32_e32 v44, 0
	v_mov_b32_e32 v45, 0
	v_mov_b32_e32 v46, 0
	v_mov_b32_e32 v47, 0
	v_mov_b32_e32 v48, 0
	v_mov_b32_e32 v49, 0
	v_mov_b32_e32 v50, 0
	v_mov_b32_e32 v51, 0
	v_mov_b32_e32 v52, 0
	v_mov_b32_e32 v53, 0
	v_mov_b32_e32 v54, 0
	v_mov_b32_e32 v55, 0
	v_mov_b32_e32 v56, 0
	v_mov_b32_e32 v57, 0
	v_mov_b32_e32 v58, 0
	v_mov_b32_e32 v59, 0
	v_mov_b32_e32 v60, 0
	v_mov_b32_e32 v61, 0
	v_mov_b32_e32 v62, 0
	v_mov_b32_e32 v63, 0
	v_mov_b32_e32 v64, 0
	v_mov_b32_e32 v65, 0
	v_mov_b32_e32 v66, 0
	v_mov_b32_e32 v67, 0
	v_mov_b32_e32 v68, 0
	v_mov_b32_e32 v69, 0
	v_mov_b32_e32 v70, 0
	v_mov_b32_e32 v71, 0
	v_mov_b32_e32 v72, 0
	v_mov_b32_e32 v73, 0
	v_mov_b32_e32 v74, 0
	v_mov_b32_e32 v75, 0
	v_mov_b32_e32 v76, 0
	v_mov_b32_e32 v77, 0
	v_mov_b32_e32 v78, 0
	v_mov_b32_e32 v79, 0
	v_mov_b32_e32 v80, 0
	v_mov_b32_e32 v81, 0
	v_mov_b32_e32 v82, 0
	v_mov_b32_e32 v83, 0
	v_mov_b32_e32 v84, 0
	v_mov_b32_e32 v85, 0
	v_mov_b32_e32 v86, 0
	v_mov_b32_e32 v87, 0
	v_mov_b32_e32 v88, 0
	v_mov_b32_e32 v89, 0
	v_mov_b32_e32 v90, 0
	v_mov_b32_e32 v91, 0
	v_mov_b32_e32 v92, 0
	v_mov_b32_e32 v93, 0
	v_mov_b32_e32 v94, 0
	v_mov_b32_e32 v95, 0
	v_mov_b32_e32 v96, 0
	v_mov_b32_e32 v97, 0
	v_mov_b32_e32 v98, 0
	v_mov_b32_e32 v99, 0
	v_mov_b32_e32 v100, 0
	v_mov_b32_e32 v101, 0
	v_mov_b32_e32 v102, 0
	v_mov_b32_e32 v103, 0
	v_mov_b32_e32 v104, 0
	v_mov_b32_e32 v105, 0
	v_mov_b32_e32 v106, 0
	v_mov_b32_e32 v107, 0
	v_mov_b32_e32 v108, 0
	v_mov_b32_e32 v109, 0
	v_mov_b32_e32 v110, 0
	v_mov_b32_e32 v111, 0
	v_mov_b32_e32 v112, 0
	v_mov_b32_e32 v113, 0
	v_mov_b32_e32 v114, 0
	v_mov_b32_e32 v115, 0
	v_mov_b32_e32 v116, 0
	v_mov_b32_e32 v117, 0
	v_mov_b32_e32 v118, 0
	v_mov_b32_e32 v119, 0
	v_mov_b32_e32 v120, 0
	v_mov_b32_e32 v121, 0
	v_mov_b32_e32 v122, 0
	v_mov_b32_e32 v123, 0
	v_mov_b32_e32 v124, 0
	v_mov_b32_e32 v125, 0
	v_mov_b32_e32 v126, 0
	v_mov_b32_e32 v127, 0
	s_mov_b32 s50, 0
	s_waitcnt vmcnt(32)
	s_branch .Lbig_k_in

.Lbig_k_in:
	s_barrier
	ds_read_b128 v[160:163], v198 offset:0
	ds_read_b128 v[164:167], v198 offset:2048
	ds_read_b128 v[168:171], v198 offset:4096
	ds_read_b128 v[172:175], v198 offset:6144
	ds_read_b128 v[128:131], v196 offset:0
	ds_read_b128 v[132:135], v196 offset:2048
	ds_read_b128 v[136:139], v196 offset:4096
	ds_read_b128 v[140:143], v196 offset:6144
	ds_read_b128 v[144:147], v196 offset:8192
	ds_read_b128 v[148:151], v196 offset:10240
	ds_read_b128 v[152:155], v196 offset:12288
	ds_read_b128 v[156:159], v196 offset:14336
	ds_read_b128 v[176:179], v200 offset:0
	ds_read_b128 v[180:183], v200 offset:2048
	ds_read_b128 v[184:187], v200 offset:4096
	ds_read_b128 v[188:191], v200 offset:6144
	ds_read_b128 v[204:207], v197 offset:0
	ds_read_b128 v[208:211], v197 offset:2048
	ds_read_b128 v[212:215], v197 offset:4096
	ds_read_b128 v[216:219], v197 offset:6144
	ds_read_b128 v[220:223], v197 offset:8192
	ds_read_b128 v[224:227], v197 offset:10240
	ds_read_b128 v[228:231], v197 offset:12288
	ds_read_b128 v[232:235], v197 offset:14336
	s_waitcnt lgkmcnt(0)
	s_barrier
	s_add_u32 m0, s32, 0x0
	s_nop 0
	global_load_lds_dwordx4 v192, s[36:37]
	s_add_u32 m0, s32, 0x1000
	s_nop 0
	global_load_lds_dwordx4 v193, s[36:37]
	s_add_u32 m0, s32, 0x2000
	s_nop 0
	global_load_lds_dwordx4 v194, s[36:37]
	s_add_u32 m0, s32, 0x3000
	s_nop 0
	global_load_lds_dwordx4 v195, s[36:37]
	s_add_u32 m0, s32, 0x4000
	s_nop 0
	global_load_lds_dwordx4 v192, s[40:41]
	s_add_u32 m0, s32, 0x5000
	s_nop 0
	global_load_lds_dwordx4 v193, s[40:41]
	s_add_u32 m0, s32, 0x6000
	s_nop 0
	global_load_lds_dwordx4 v194, s[40:41]
	s_add_u32 m0, s32, 0x7000
	s_nop 0
	global_load_lds_dwordx4 v195, s[40:41]
	s_add_u32 m0, s32, 0x8000
	s_nop 0
	global_load_lds_dwordx4 v192, s[44:45]
	s_add_u32 m0, s32, 0x9000
	s_nop 0
	global_load_lds_dwordx4 v193, s[44:45]
	s_add_u32 m0, s32, 0xa000
	s_nop 0
	global_load_lds_dwordx4 v194, s[44:45]
	s_add_u32 m0, s32, 0xb000
	s_nop 0
	global_load_lds_dwordx4 v195, s[44:45]
	s_add_u32 s36, s36, 0x80
	s_addc_u32 s37, s37, 0
	s_add_u32 s40, s40, 0x80
	s_addc_u32 s41, s41, 0
	s_add_u32 s44, s44, 0x80
	s_addc_u32 s45, s45, 0
	s_setprio 1
	v_mfma_f32_16x16x32_bf16 v[0:3], v[160:163], v[128:131], v[0:3]
	v_mfma_f32_16x16x32_bf16 v[4:7], v[164:167], v[128:131], v[4:7]
	v_mfma_f32_16x16x32_bf16 v[8:11], v[168:171], v[128:131], v[8:11]
	v_mfma_f32_16x16x32_bf16 v[12:15], v[172:175], v[128:131], v[12:15]
	v_mfma_f32_16x16x32_bf16 v[16:19], v[160:163], v[132:135], v[16:19]
	v_mfma_f32_16x16x32_bf16 v[20:23], v[164:167], v[132:135], v[20:23]
	v_mfma_f32_16x16x32_bf16 v[24:27], v[168:171], v[132:135], v[24:27]
	v_mfma_f32_16x16x32_bf16 v[28:31], v[172:175], v[132:135], v[28:31]
	v_mfma_f32_16x16x32_bf16 v[32:35], v[160:163], v[136:139], v[32:35]
	v_mfma_f32_16x16x32_bf16 v[36:39], v[164:167], v[136:139], v[36:39]
	v_mfma_f32_16x16x32_bf16 v[40:43], v[168:171], v[136:139], v[40:43]
	v_mfma_f32_16x16x32_bf16 v[44:47], v[172:175], v[136:139], v[44:47]
	v_mfma_f32_16x16x32_bf16 v[48:51], v[160:163], v[140:143], v[48:51]
	v_mfma_f32_16x16x32_bf16 v[52:55], v[164:167], v[140:143], v[52:55]
	v_mfma_f32_16x16x32_bf16 v[56:59], v[168:171], v[140:143], v[56:59]
	v_mfma_f32_16x16x32_bf16 v[60:63], v[172:175], v[140:143], v[60:63]
	v_mfma_f32_16x16x32_bf16 v[64:67], v[160:163], v[144:147], v[64:67]
	v_mfma_f32_16x16x32_bf16 v[68:71], v[164:167], v[144:147], v[68:71]
	v_mfma_f32_16x16x32_bf16 v[72:75], v[168:171], v[144:147], v[72:75]
	v_mfma_f32_16x16x32_bf16 v[76:79], v[172:175], v[144:147], v[76:79]
	v_mfma_f32_16x16x32_bf16 v[80:83], v[160:163], v[148:151], v[80:83]
	v_mfma_f32_16x16x32_bf16 v[84:87], v[164:167], v[148:151], v[84:87]
	v_mfma_f32_16x16x32_bf16 v[88:91], v[168:171], v[148:151], v[88:91]
	v_mfma_f32_16x16x32_bf16 v[92:95], v[172:175], v[148:151], v[92:95]
	v_mfma_f32_16x16x32_bf16 v[96:99], v[160:163], v[152:155], v[96:99]
	v_mfma_f32_16x16x32_bf16 v[100:103], v[164:167], v[152:155], v[100:103]
	v_mfma_f32_16x16x32_bf16 v[104:107], v[168:171], v[152:155], v[104:107]
	v_mfma_f32_16x16x32_bf16 v[108:111], v[172:175], v[152:155], v[108:111]
	v_mfma_f32_16x16x32_bf16 v[112:115], v[160:163], v[156:159], v[112:115]
	v_mfma_f32_16x16x32_bf16 v[116:119], v[164:167], v[156:159], v[116:119]
	v_mfma_f32_16x16x32_bf16 v[120:123], v[168:171], v[156:159], v[120:123]
	v_mfma_f32_16x16x32_bf16 v[124:127], v[172:175], v[156:159], v[124:127]
	v_mfma_f32_16x16x32_bf16 v[0:3], v[176:179], v[204:207], v[0:3]
	v_mfma_f32_16x16x32_bf16 v[4:7], v[180:183], v[204:207], v[4:7]
	v_mfma_f32_16x16x32_bf16 v[8:11], v[184:187], v[204:207], v[8:11]
	v_mfma_f32_16x16x32_bf16 v[12:15], v[188:191], v[204:207], v[12:15]
	v_mfma_f32_16x16x32_bf16 v[16:19], v[176:179], v[208:211], v[16:19]
	v_mfma_f32_16x16x32_bf16 v[20:23], v[180:183], v[208:211], v[20:23]
	v_mfma_f32_16x16x32_bf16 v[24:27], v[184:187], v[208:211], v[24:27]
	v_mfma_f32_16x16x32_bf16 v[28:31], v[188:191], v[208:211], v[28:31]
	v_mfma_f32_16x16x32_bf16 v[32:35], v[176:179], v[212:215], v[32:35]
	v_mfma_f32_16x16x32_bf16 v[36:39], v[180:183], v[212:215], v[36:39]
	v_mfma_f32_16x16x32_bf16 v[40:43], v[184:187], v[212:215], v[40:43]
	v_mfma_f32_16x16x32_bf16 v[44:47], v[188:191], v[212:215], v[44:47]
	v_mfma_f32_16x16x32_bf16 v[48:51], v[176:179], v[216:219], v[48:51]
	v_mfma_f32_16x16x32_bf16 v[52:55], v[180:183], v[216:219], v[52:55]
	v_mfma_f32_16x16x32_bf16 v[56:59], v[184:187], v[216:219], v[56:59]
	v_mfma_f32_16x16x32_bf16 v[60:63], v[188:191], v[216:219], v[60:63]
	v_mfma_f32_16x16x32_bf16 v[64:67], v[176:179], v[220:223], v[64:67]
	v_mfma_f32_16x16x32_bf16 v[68:71], v[180:183], v[220:223], v[68:71]
	v_mfma_f32_16x16x32_bf16 v[72:75], v[184:187], v[220:223], v[72:75]
	v_mfma_f32_16x16x32_bf16 v[76:79], v[188:191], v[220:223], v[76:79]
	v_mfma_f32_16x16x32_bf16 v[80:83], v[176:179], v[224:227], v[80:83]
	v_mfma_f32_16x16x32_bf16 v[84:87], v[180:183], v[224:227], v[84:87]
	v_mfma_f32_16x16x32_bf16 v[88:91], v[184:187], v[224:227], v[88:91]
	v_mfma_f32_16x16x32_bf16 v[92:95], v[188:191], v[224:227], v[92:95]
	v_mfma_f32_16x16x32_bf16 v[96:99], v[176:179], v[228:231], v[96:99]
	v_mfma_f32_16x16x32_bf16 v[100:103], v[180:183], v[228:231], v[100:103]
	v_mfma_f32_16x16x32_bf16 v[104:107], v[184:187], v[228:231], v[104:107]
	v_mfma_f32_16x16x32_bf16 v[108:111], v[188:191], v[228:231], v[108:111]
	v_mfma_f32_16x16x32_bf16 v[112:115], v[176:179], v[232:235], v[112:115]
	v_mfma_f32_16x16x32_bf16 v[116:119], v[180:183], v[232:235], v[116:119]
	v_mfma_f32_16x16x32_bf16 v[120:123], v[184:187], v[232:235], v[120:123]
	v_mfma_f32_16x16x32_bf16 v[124:127], v[188:191], v[232:235], v[124:127]
	s_setprio 0
	s_add_i32 s50, s50, 1
	s_cmp_lt_u32 s50, 31
	s_cbranch_scc1 .Lbig_k
	s_waitcnt vmcnt(0)
	s_barrier
	ds_read_b128 v[160:163], v198 offset:0
	ds_read_b128 v[164:167], v198 offset:2048
	ds_read_b128 v[168:171], v198 offset:4096
	ds_read_b128 v[172:175], v198 offset:6144
	ds_read_b128 v[128:131], v196 offset:0
	ds_read_b128 v[132:135], v196 offset:2048
	ds_read_b128 v[136:139], v196 offset:4096
	ds_read_b128 v[140:143], v196 offset:6144
	ds_read_b128 v[144:147], v196 offset:8192
	ds_read_b128 v[148:151], v196 offset:10240
	ds_read_b128 v[152:155], v196 offset:12288
	ds_read_b128 v[156:159], v196 offset:14336
	ds_read_b128 v[176:179], v200 offset:0
	ds_read_b128 v[180:183], v200 offset:2048
	ds_read_b128 v[184:187], v200 offset:4096
	ds_read_b128 v[188:191], v200 offset:6144
	ds_read_b128 v[204:207], v197 offset:0
	ds_read_b128 v[208:211], v197 offset:2048
	ds_read_b128 v[212:215], v197 offset:4096
	ds_read_b128 v[216:219], v197 offset:6144
	ds_read_b128 v[220:223], v197 offset:8192
	ds_read_b128 v[224:227], v197 offset:10240
	ds_read_b128 v[228:231], v197 offset:12288
	ds_read_b128 v[232:235], v197 offset:14336
	s_waitcnt lgkmcnt(0)
	s_cmp_ge_u32 s91, 0x1400
	s_cbranch_scc1 .Lbig_nonext
	s_barrier
	s_mov_b64 s[36:37], s[46:47]
	s_mov_b64 s[44:45], s[48:49]
	s_add_u32 s40, s36, 0x80000
	s_addc_u32 s41, s37, 0
	s_add_u32 m0, s32, 0x0
	s_nop 0
	global_load_lds_dwordx4 v192, s[36:37]
	s_add_u32 m0, s32, 0x1000
	s_nop 0
	global_load_lds_dwordx4 v193, s[36:37]
	s_add_u32 m0, s32, 0x2000
	s_nop 0
	global_load_lds_dwordx4 v194, s[36:37]
	s_add_u32 m0, s32, 0x3000
	s_nop 0
	global_load_lds_dwordx4 v195, s[36:37]
	s_add_u32 m0, s32, 0x4000
	s_nop 0
	global_load_lds_dwordx4 v192, s[40:41]
	s_add_u32 m0, s32, 0x5000
	s_nop 0
	global_load_lds_dwordx4 v193, s[40:41]
	s_add_u32 m0, s32, 0x6000
	s_nop 0
	global_load_lds_dwordx4 v194, s[40:41]
	s_add_u32 m0, s32, 0x7000
	s_nop 0
	global_load_lds_dwordx4 v195, s[40:41]
	s_add_u32 m0, s32, 0x8000
	s_nop 0
	global_load_lds_dwordx4 v192, s[44:45]
	s_add_u32 m0, s32, 0x9000
	s_nop 0
	global_load_lds_dwordx4 v193, s[44:45]
	s_add_u32 m0, s32, 0xa000
	s_nop 0
	global_load_lds_dwordx4 v194, s[44:45]
	s_add_u32 m0, s32, 0xb000
	s_nop 0
	global_load_lds_dwordx4 v195, s[44:45]
	s_add_u32 s36, s36, 0x80
	s_addc_u32 s37, s37, 0
	s_add_u32 s40, s40, 0x80
	s_addc_u32 s41, s41, 0
	s_add_u32 s44, s44, 0x80
	s_addc_u32 s45, s45, 0
.Lbig_nonext:
	s_setprio 1
	v_mfma_f32_16x16x32_bf16 v[0:3], v[160:163], v[128:131], v[0:3]
	v_mfma_f32_16x16x32_bf16 v[4:7], v[164:167], v[128:131], v[4:7]
	v_mfma_f32_16x16x32_bf16 v[8:11], v[168:171], v[128:131], v[8:11]
	v_mfma_f32_16x16x32_bf16 v[12:15], v[172:175], v[128:131], v[12:15]
	v_mfma_f32_16x16x32_bf16 v[16:19], v[160:163], v[132:135], v[16:19]
	v_mfma_f32_16x16x32_bf16 v[20:23], v[164:167], v[132:135], v[20:23]
	v_mfma_f32_16x16x32_bf16 v[24:27], v[168:171], v[132:135], v[24:27]
	v_mfma_f32_16x16x32_bf16 v[28:31], v[172:175], v[132:135], v[28:31]
	v_mfma_f32_16x16x32_bf16 v[32:35], v[160:163], v[136:139], v[32:35]
	v_mfma_f32_16x16x32_bf16 v[36:39], v[164:167], v[136:139], v[36:39]
	v_mfma_f32_16x16x32_bf16 v[40:43], v[168:171], v[136:139], v[40:43]
	v_mfma_f32_16x16x32_bf16 v[44:47], v[172:175], v[136:139], v[44:47]
	v_mfma_f32_16x16x32_bf16 v[48:51], v[160:163], v[140:143], v[48:51]
	v_mfma_f32_16x16x32_bf16 v[52:55], v[164:167], v[140:143], v[52:55]
	v_mfma_f32_16x16x32_bf16 v[56:59], v[168:171], v[140:143], v[56:59]
	v_mfma_f32_16x16x32_bf16 v[60:63], v[172:175], v[140:143], v[60:63]
	v_mfma_f32_16x16x32_bf16 v[64:67], v[160:163], v[144:147], v[64:67]
	v_mfma_f32_16x16x32_bf16 v[68:71], v[164:167], v[144:147], v[68:71]
	v_mfma_f32_16x16x32_bf16 v[72:75], v[168:171], v[144:147], v[72:75]
	v_mfma_f32_16x16x32_bf16 v[76:79], v[172:175], v[144:147], v[76:79]
	v_mfma_f32_16x16x32_bf16 v[80:83], v[160:163], v[148:151], v[80:83]
	v_mfma_f32_16x16x32_bf16 v[84:87], v[164:167], v[148:151], v[84:87]
	v_mfma_f32_16x16x32_bf16 v[88:91], v[168:171], v[148:151], v[88:91]
	v_mfma_f32_16x16x32_bf16 v[92:95], v[172:175], v[148:151], v[92:95]
	v_mfma_f32_16x16x32_bf16 v[96:99], v[160:163], v[152:155], v[96:99]
	v_mfma_f32_16x16x32_bf16 v[100:103], v[164:167], v[152:155], v[100:103]
	v_mfma_f32_16x16x32_bf16 v[104:107], v[168:171], v[152:155], v[104:107]
	v_mfma_f32_16x16x32_bf16 v[108:111], v[172:175], v[152:155], v[108:111]
	v_mfma_f32_16x16x32_bf16 v[112:115], v[160:163], v[156:159], v[112:115]
	v_mfma_f32_16x16x32_bf16 v[116:119], v[164:167], v[156:159], v[116:119]
	v_mfma_f32_16x16x32_bf16 v[120:123], v[168:171], v[156:159], v[120:123]
	v_mfma_f32_16x16x32_bf16 v[124:127], v[172:175], v[156:159], v[124:127]
	v_mfma_f32_16x16x32_bf16 v[0:3], v[176:179], v[204:207], v[0:3]
	v_mfma_f32_16x16x32_bf16 v[4:7], v[180:183], v[204:207], v[4:7]
	v_mfma_f32_16x16x32_bf16 v[8:11], v[184:187], v[204:207], v[8:11]
	v_mfma_f32_16x16x32_bf16 v[12:15], v[188:191], v[204:207], v[12:15]
	v_mfma_f32_16x16x32_bf16 v[16:19], v[176:179], v[208:211], v[16:19]
	v_mfma_f32_16x16x32_bf16 v[20:23], v[180:183], v[208:211], v[20:23]
	v_mfma_f32_16x16x32_bf16 v[24:27], v[184:187], v[208:211], v[24:27]
	v_mfma_f32_16x16x32_bf16 v[28:31], v[188:191], v[208:211], v[28:31]
	v_mfma_f32_16x16x32_bf16 v[32:35], v[176:179], v[212:215], v[32:35]
	v_mfma_f32_16x16x32_bf16 v[36:39], v[180:183], v[212:215], v[36:39]
	v_mfma_f32_16x16x32_bf16 v[40:43], v[184:187], v[212:215], v[40:43]
	v_mfma_f32_16x16x32_bf16 v[44:47], v[188:191], v[212:215], v[44:47]
	v_mfma_f32_16x16x32_bf16 v[48:51], v[176:179], v[216:219], v[48:51]
	v_mfma_f32_16x16x32_bf16 v[52:55], v[180:183], v[216:219], v[52:55]
	v_mfma_f32_16x16x32_bf16 v[56:59], v[184:187], v[216:219], v[56:59]
	v_mfma_f32_16x16x32_bf16 v[60:63], v[188:191], v[216:219], v[60:63]
	v_mfma_f32_16x16x32_bf16 v[64:67], v[176:179], v[220:223], v[64:67]
	v_mfma_f32_16x16x32_bf16 v[68:71], v[180:183], v[220:223], v[68:71]
	v_mfma_f32_16x16x32_bf16 v[72:75], v[184:187], v[220:223], v[72:75]
	v_mfma_f32_16x16x32_bf16 v[76:79], v[188:191], v[220:223], v[76:79]
	v_mfma_f32_16x16x32_bf16 v[80:83], v[176:179], v[224:227], v[80:83]
	v_mfma_f32_16x16x32_bf16 v[84:87], v[180:183], v[224:227], v[84:87]
	v_mfma_f32_16x16x32_bf16 v[88:91], v[184:187], v[224:227], v[88:91]
	v_mfma_f32_16x16x32_bf16 v[92:95], v[188:191], v[224:227], v[92:95]
	v_mfma_f32_16x16x32_bf16 v[96:99], v[176:179], v[228:231], v[96:99]
	v_mfma_f32_16x16x32_bf16 v[100:103], v[180:183], v[228:231], v[100:103]
	v_mfma_f32_16x16x32_bf16 v[104:107], v[184:187], v[228:231], v[104:107]
	v_mfma_f32_16x16x32_bf16 v[108:111], v[188:191], v[228:231], v[108:111]
	v_mfma_f32_16x16x32_bf16 v[112:115], v[176:179], v[232:235], v[112:115]
	v_mfma_f32_16x16x32_bf16 v[116:119], v[180:183], v[232:235], v[116:119]
	v_mfma_f32_16x16x32_bf16 v[120:123], v[184:187], v[232:235], v[120:123]
	v_mfma_f32_16x16x32_bf16 v[124:127], v[188:191], v[232:235], v[124:127]
	s_setprio 0
	s_lshr_b32 s51, s90, 6
	s_lshl_b32 s51, s51, 7
	s_and_b32 s17, s90, 63
	s_lshl_b32 s17, s17, 8
	s_mov_b32 s16, 0x1b00
	s_mov_b32 s18, 0
	s_mov_b32 s19, 0
	s_cmp_lt_u32 s51, 0xd80
	s_cbranch_scc1 .Lbig_reg
	s_mov_b32 s16, 0x1900
	s_mov_b32 s18, 0x6c00000
	s_mov_b32 s19, 0xd80
	s_cmp_lt_u32 s51, 0x1a00
	s_cbranch_scc1 .Lbig_reg
	s_mov_b32 s16, 0x2000
	s_mov_b32 s18, 0xd000000
	s_mov_b32 s19, 0x1a00
.Lbig_reg:
	s_sub_u32 s51, s51, s19
	s_lshl_b32 s51, s51, 1
	s_mul_i32 s17, s17, s16
	s_add_u32 s17, s17, s51
	s_add_u32 s17, s17, s18
	s_add_u32 s14, s94, s17
	s_addc_u32 s15, s95, 0
	s_lshl_b32 s16, s16, 4
	v_mul_lo_u32 v203, v201, s16
	v_lshrrev_b32_e32 v203, 4, v203
	v_add_u32_e32 v203, v203, v202
	v_cvt_pk_bf16_f32 v240, v0, v1
	v_cvt_pk_bf16_f32 v241, v2, v3
	global_store_dwordx2 v203, v[240:241], s[14:15]
	v_cvt_pk_bf16_f32 v236, v4, v5
	v_cvt_pk_bf16_f32 v237, v6, v7
	global_store_dwordx2 v203, v[236:237], s[14:15] offset:32
	v_cvt_pk_bf16_f32 v240, v8, v9
	v_cvt_pk_bf16_f32 v241, v10, v11
	global_store_dwordx2 v203, v[240:241], s[14:15] offset:64
	v_cvt_pk_bf16_f32 v236, v12, v13
	v_cvt_pk_bf16_f32 v237, v14, v15
	global_store_dwordx2 v203, v[236:237], s[14:15] offset:96
	s_add_u32 s14, s14, s16
	s_addc_u32 s15, s15, 0
	v_cvt_pk_bf16_f32 v240, v16, v17
	v_cvt_pk_bf16_f32 v241, v18, v19
	global_store_dwordx2 v203, v[240:241], s[14:15]
	v_cvt_pk_bf16_f32 v236, v20, v21
	v_cvt_pk_bf16_f32 v237, v22, v23
	global_store_dwordx2 v203, v[236:237], s[14:15] offset:32
	v_cvt_pk_bf16_f32 v240, v24, v25
	v_cvt_pk_bf16_f32 v241, v26, v27
	global_store_dwordx2 v203, v[240:241], s[14:15] offset:64
	v_cvt_pk_bf16_f32 v236, v28, v29
	v_cvt_pk_bf16_f32 v237, v30, v31
	global_store_dwordx2 v203, v[236:237], s[14:15] offset:96
	s_add_u32 s14, s14, s16
	s_addc_u32 s15, s15, 0
	v_cvt_pk_bf16_f32 v240, v32, v33
	v_cvt_pk_bf16_f32 v241, v34, v35
	global_store_dwordx2 v203, v[240:241], s[14:15]
	v_cvt_pk_bf16_f32 v236, v36, v37
	v_cvt_pk_bf16_f32 v237, v38, v39
	global_store_dwordx2 v203, v[236:237], s[14:15] offset:32
	v_cvt_pk_bf16_f32 v240, v40, v41
	v_cvt_pk_bf16_f32 v241, v42, v43
	global_store_dwordx2 v203, v[240:241], s[14:15] offset:64
	v_cvt_pk_bf16_f32 v236, v44, v45
	v_cvt_pk_bf16_f32 v237, v46, v47
	global_store_dwordx2 v203, v[236:237], s[14:15] offset:96
	s_add_u32 s14, s14, s16
	s_addc_u32 s15, s15, 0
	v_cvt_pk_bf16_f32 v240, v48, v49
	v_cvt_pk_bf16_f32 v241, v50, v51
	global_store_dwordx2 v203, v[240:241], s[14:15]
	v_cvt_pk_bf16_f32 v236, v52, v53
	v_cvt_pk_bf16_f32 v237, v54, v55
	global_store_dwordx2 v203, v[236:237], s[14:15] offset:32
	v_cvt_pk_bf16_f32 v240, v56, v57
	v_cvt_pk_bf16_f32 v241, v58, v59
	global_store_dwordx2 v203, v[240:241], s[14:15] offset:64
	v_cvt_pk_bf16_f32 v236, v60, v61
	v_cvt_pk_bf16_f32 v237, v62, v63
	global_store_dwordx2 v203, v[236:237], s[14:15] offset:96
	s_add_u32 s14, s14, s16
	s_addc_u32 s15, s15, 0
	v_cvt_pk_bf16_f32 v240, v64, v65
	v_cvt_pk_bf16_f32 v241, v66, v67
	global_store_dwordx2 v203, v[240:241], s[14:15]
	v_cvt_pk_bf16_f32 v236, v68, v69
	v_cvt_pk_bf16_f32 v237, v70, v71
	global_store_dwordx2 v203, v[236:237], s[14:15] offset:32
	v_cvt_pk_bf16_f32 v240, v72, v73
	v_cvt_pk_bf16_f32 v241, v74, v75
	global_store_dwordx2 v203, v[240:241], s[14:15] offset:64
	v_cvt_pk_bf16_f32 v236, v76, v77
	v_cvt_pk_bf16_f32 v237, v78, v79
	global_store_dwordx2 v203, v[236:237], s[14:15] offset:96
	s_add_u32 s14, s14, s16
	s_addc_u32 s15, s15, 0
	v_cvt_pk_bf16_f32 v240, v80, v81
	v_cvt_pk_bf16_f32 v241, v82, v83
	global_store_dwordx2 v203, v[240:241], s[14:15]
	v_cvt_pk_bf16_f32 v236, v84, v85
	v_cvt_pk_bf16_f32 v237, v86, v87
	global_store_dwordx2 v203, v[236:237], s[14:15] offset:32
	v_cvt_pk_bf16_f32 v240, v88, v89
	v_cvt_pk_bf16_f32 v241, v90, v91
	global_store_dwordx2 v203, v[240:241], s[14:15] offset:64
	v_cvt_pk_bf16_f32 v236, v92, v93
	v_cvt_pk_bf16_f32 v237, v94, v95
	global_store_dwordx2 v203, v[236:237], s[14:15] offset:96
	s_add_u32 s14, s14, s16
	s_addc_u32 s15, s15, 0
	v_cvt_pk_bf16_f32 v240, v96, v97
	v_cvt_pk_bf16_f32 v241, v98, v99
	global_store_dwordx2 v203, v[240:241], s[14:15]
	v_cvt_pk_bf16_f32 v236, v100, v101
	v_cvt_pk_bf16_f32 v237, v102, v103
	global_store_dwordx2 v203, v[236:237], s[14:15] offset:32
	v_cvt_pk_bf16_f32 v240, v104, v105
	v_cvt_pk_bf16_f32 v241, v106, v107
	global_store_dwordx2 v203, v[240:241], s[14:15] offset:64
	v_cvt_pk_bf16_f32 v236, v108, v109
	v_cvt_pk_bf16_f32 v237, v110, v111
	global_store_dwordx2 v203, v[236:237], s[14:15] offset:96
	s_add_u32 s14, s14, s16
	s_addc_u32 s15, s15, 0
	v_cvt_pk_bf16_f32 v240, v112, v113
	v_cvt_pk_bf16_f32 v241, v114, v115
	global_store_dwordx2 v203, v[240:241], s[14:15]
	v_cvt_pk_bf16_f32 v236, v116, v117
	v_cvt_pk_bf16_f32 v237, v118, v119
	global_store_dwordx2 v203, v[236:237], s[14:15] offset:32
	v_cvt_pk_bf16_f32 v240, v120, v121
	v_cvt_pk_bf16_f32 v241, v122, v123
	global_store_dwordx2 v203, v[240:241], s[14:15] offset:64
	v_cvt_pk_bf16_f32 v236, v124, v125
	v_cvt_pk_bf16_f32 v237, v126, v127
	global_store_dwordx2 v203, v[236:237], s[14:15] offset:96
	s_add_u32 s90, s90, 0x200
	s_cmp_lt_u32 s90, 0x1400
	s_cbranch_scc1 .Lbig_tile
	s_waitcnt vmcnt(0)
	s_mov_b32 s91, 1
.Lbig_skip:
	v_mov_b32_e32 v0, v199
	v_lshrrev_b32_e32 v2, 4, v0
	v_xor_b32_e32 v2, v2, v0
	v_lshlrev_b32_e32 v2, 4, v2
	v_readlane_b32 s0, v242, 50
	v_and_b32_e32 v64, 0x70, v2
	v_mov_b32_e32 v65, 0
	v_readlane_b32 s1, v242, 51
	v_ashrrev_i32_e32 v98, 3, v0
	v_lshl_add_u64 v[68:69], s[58:59], 0, v[64:65]
	v_lshl_add_u64 v[66:67], s[0:1], 0, v[64:65]
	v_readlane_b32 s0, v242, 45
	s_mov_b32 s10, s0
	s_lshl_b32 s0, s0, 4
	v_readlane_b32 s1, v242, 46
	s_and_b32 s0, s0, 0x70
	s_mulk_i32 s0, 0x54
	s_ashr_i32 s1, s10, 3
	s_add_i32 s0, s0, s1
	s_mul_hi_i32 s1, s0, 0x30c30c31
	s_lshr_b32 s2, s1, 31
	s_ashr_i32 s1, s1, 7
	s_add_i32 s2, s1, s2
	s_mul_i32 s1, s2, 0x2a0
	s_sub_i32 s3, s0, s1
	s_sext_i32_i16 s0, s3
	s_bfe_u32 s0, s0, 0x3001c
	s_add_i32 s4, s3, s0
	s_sext_i32_i16 s0, s4
	s_lshl_b32 s0, s0, 4
	s_and_b32 s4, s4, 0xfff8
	s_and_b32 s81, s0, 0xffffff80
	s_sub_i32 s3, s3, s4
	v_add_u32_e32 v2, s81, v98
	s_sext_i32_i16 s3, s3
	v_ashrrev_i32_e32 v3, 31, v2
	s_lshl_b32 s3, s3, 7
	s_lshl_b32 s2, s2, 10
	v_lshlrev_b64 v[2:3], 12, v[2:3]
	s_add_i32 s8, s3, s2
	v_lshl_add_u64 v[70:71], v[68:69], 0, v[2:3]
	v_add_u32_e32 v2, s8, v98
	v_ashrrev_i32_e32 v3, 31, v2
	v_lshlrev_b64 v[2:3], 12, v[2:3]
	v_and_b32_e32 v1, 15, v0
	v_and_b32_e32 v4, 64, v0
	s_mov_b64 s[0:1], 0x60000
	v_lshl_add_u64 v[74:75], v[66:67], 0, v[2:3]
	s_mov_b64 s[2:3], 0x40000
	s_mov_b64 s[14:15], 0x20000
	v_ashrrev_i32_e32 v2, 1, v0
	s_movk_i32 s4, 0xffc0
	v_lshrrev_b32_e32 v0, 2, v0
	s_movk_i32 s18, 0xcc00
	s_movk_i32 s20, 0xe500
	s_movk_i32 s22, 0xcc20
	s_movk_i32 s26, 0xe520
	s_movk_i32 s30, 0xcc40
	s_movk_i32 s34, 0xe540
	s_movk_i32 s38, 0xcc60
	s_movk_i32 s42, 0xe560
	v_lshl_add_u64 v[72:73], v[70:71], 0, s[0:1]
	v_lshl_add_u64 v[76:77], v[74:75], 0, s[0:1]
	v_lshl_add_u64 v[78:79], v[70:71], 0, s[2:3]
	v_lshl_add_u64 v[80:81], v[74:75], 0, s[2:3]
	v_lshl_add_u64 v[82:83], v[70:71], 0, s[14:15]
	v_lshl_add_u64 v[84:85], v[74:75], 0, s[14:15]
	v_and_or_b32 v99, v2, s4, v1
	v_and_or_b32 v100, v0, 12, v4
	s_mov_b64 s[6:7], -1
	s_mov_b64 s[16:17], 0x80
	s_movk_i32 s25, 0x1900
	s_movk_i32 s33, 0x1b00
	s_movk_i32 s59, 0xd7f
	s_mov_b32 s19, -1
	s_mov_b32 s21, -1
	s_mov_b32 s23, -1
	s_mov_b32 s27, -1
	s_mov_b32 s31, -1
	s_mov_b32 s35, -1
	s_mov_b32 s39, -1
	s_mov_b32 s43, -1
	s_mov_b64 s[52:53], 0x60
	s_mov_b32 s80, s10
	s_mov_b32 s86, s8
	s_mov_b32 s87, s81
	s_cmp_eq_u32 s91, 0
	s_cbranch_scc1 .Lbig_noovr
	v_readlane_b32 s90, v242, 45
	s_nop 3
	s_and_b32 s8, s90, 0x7f
	s_lshl_b32 s8, s8, 7
	s_lshr_b32 s81, s90, 7
	s_lshl_b32 s81, s81, 7
	s_add_u32 s81, s81, 0x2800
	s_mov_b32 s86, s8
	s_mov_b32 s87, s81
	s_movk_i32 s80, 0x2a00
.Lbig_noovr:
	s_branch .LBB0_119
